# P0 poolfold staggered: odd workgroups fold after the streaming loops (HBM busy from t=0)
# baseline (speedup 1.0000x reference)
; #define LAS __attribute__((address_space(3)))
; __device__ __forceinline__ void poolfold_block(const Args& p, LAS unsigned char* lds, int item, int tid) {
;     const int g = item >> 6, nb = item & 63;
;     LAS float* PW = (LAS float*)lds;
;     LAS float* WO = (LAS float*)(lds + 128 * 132 * 4);
;     const float* pw = p.pool_w() + (size_t)g * 16384;
; #pragma unroll
;     for (int i = 0; i < 8; ++i) { const int idx = tid + 512 * i; *(LAS f32x4*)(PW + (idx >> 5) * 132 + 4 * (idx & 31)) = ((const f32x4*)pw)[idx]; }
; #pragma unroll
;     for (int i = 0; i < 4; ++i) { const int idx = tid + 512 * i, d = idx >> 4, n = idx & 15; WO[idx] = p.w_out()[(size_t)(512 + 128 * g + d) * DM + 16 * nb + n] * p.pool_scale()[128 * g + d]; }
;     __syncthreads();
;     const int n = tid & 15, cg = tid >> 4;
; __device__ __forceinline__ void p0_prologue(const Args& p, LAS unsigned char* lds, int G, int bid, int tid) {
;     const int lane = tid & 63, wave = tid >> 6;
;     LAS float* scr = (LAS float*)(lds + wave * 16384);
;     const int gw = bid * 8 + wave, NGW = G * 8;
;     constexpr int I_IN = 16 * 48, I_K = 16 * 32, I_V = I_K, I_OUT = 8 * 32, I_Q = I_K, I_O = I_K, I_1 = 16 * 128, I_2 = 64 * 32;
;     constexpr int NITEMS = I_IN + I_K + I_V + I_OUT + I_Q + I_O + I_1 + I_2;
;     for (int it = bid; it < 256; it += G) poolfold_block(p, lds, it, tid);
.LBB0_17:
	v_writelane_b32 v242, s60, 19
	s_cmp_lt_i32 s88, 1
	s_nop 0
	v_writelane_b32 v242, s61, 20
	v_writelane_b32 v242, s62, 21
	v_writelane_b32 v242, s63, 22
	v_writelane_b32 v242, s64, 23
	v_writelane_b32 v242, s65, 24
	v_writelane_b32 v242, s66, 25
	v_writelane_b32 v242, s67, 26
	v_writelane_b32 v242, s68, 27
	v_writelane_b32 v242, s69, 28
	v_writelane_b32 v242, s70, 29
	v_writelane_b32 v242, s71, 30
	v_writelane_b32 v242, s72, 31
	v_writelane_b32 v242, s73, 32
	v_writelane_b32 v242, s74, 33
	v_writelane_b32 v242, s75, 34
	s_load_dwordx16 s[60:75], s[0:1], 0x40
	s_cselect_b64 s[0:1], -1, 0
	s_cmp_gt_i32 s89, 0
	s_cselect_b64 s[2:3], -1, 0
	s_and_b64 s[0:1], s[0:1], s[2:3]
	s_andn2_b64 vcc, exec, s[0:1]
	s_cbranch_vccnz .LBB0_158
	s_mov_b32 s98, 0
	s_cmpk_gt_i32 s94, 0xff
	s_cbranch_scc1 .LBB0_23
	s_bitcmp1_b32 s94, 0
	s_cbranch_scc1 .LBB0_23
.Lpf_entry:
	v_lshlrev_b32_e32 v0, 4, v192
	v_and_b32_e32 v0, 0x1f0, v0
	v_add_u32_e32 v1, 0, v0
	v_lshrrev_b32_e32 v0, 5, v192
	v_add_u32_e32 v5, 0x200, v192
	v_mul_u32_u24_e32 v3, 0x210, v0
	v_lshrrev_b32_e32 v0, 5, v5
	v_mul_u32_u24_e32 v7, 0x210, v0
	v_or_b32_e32 v0, 0x400, v192
	v_lshrrev_b32_e32 v2, 5, v0
	v_add_u32_e32 v6, 0x600, v192
	v_mul_u32_u24_e32 v8, 0x210, v2
	v_lshrrev_b32_e32 v2, 5, v6
	v_mul_u32_u24_e32 v9, 0x210, v2
	v_or_b32_e32 v2, 0x800, v192
	v_lshrrev_b32_e32 v4, 5, v2
	v_mul_u32_u24_e32 v10, 0x210, v4
	v_add_u32_e32 v4, 0xa00, v192
	v_lshrrev_b32_e32 v4, 5, v4
	v_mul_u32_u24_e32 v11, 0x210, v4
	v_or_b32_e32 v4, 0xc00, v192
	v_add_u32_e32 v13, 0xe00, v192
	v_lshrrev_b32_e32 v12, 5, v4
	v_lshrrev_b32_e32 v13, 5, v13
	v_and_b32_e32 v14, 15, v192
	v_lshrrev_b32_e32 v44, 4, v192
	s_add_i32 s0, 0, 0x10800
	v_mov_b32_e32 v33, 0
	v_mul_u32_u24_e32 v12, 0x210, v12
	v_mul_u32_u24_e32 v13, 0x210, v13
	v_lshl_add_u32 v45, v192, 2, s0
	v_lshrrev_b32_e32 v46, 4, v5
	v_lshl_add_u32 v47, v5, 2, s0
	v_lshl_add_u32 v49, v0, 2, s0
	v_lshrrev_b32_e32 v50, 4, v6
	v_lshl_add_u32 v51, v6, 2, s0
	s_movk_i32 s0, 0x840
	v_lshlrev_b32_e32 v6, 2, v44
	v_lshlrev_b32_e32 v5, 10, v14
	v_lshlrev_b32_e32 v32, 2, v14
	s_mov_b32 s1, 0
	v_lshrrev_b32_e32 v48, 4, v0
	v_mad_u32_u24 v52, v44, s0, 0
	s_waitcnt lgkmcnt(0)
	v_lshl_add_u64 v[34:35], s[74:75], 0, v[32:33]
	v_add_u32_e32 v53, 0, v32
	v_lshlrev_b32_e32 v36, 4, v192
	v_mov_b32_e32 v37, v33
	v_add_u32_e32 v54, v1, v3
	v_add_u32_e32 v55, v1, v7
	v_lshlrev_b32_e32 v56, 4, v0
	v_add_u32_e32 v57, v1, v8
	v_add_u32_e32 v58, v1, v9
	v_lshlrev_b32_e32 v59, 4, v2
	v_add_u32_e32 v60, v1, v10
	v_add_u32_e32 v61, v1, v11
	v_lshlrev_b32_e32 v62, 4, v4
	v_add_u32_e32 v63, v1, v12
	v_add_u32_e32 v64, v1, v13
	v_lshlrev_b32_e32 v65, 1, v5
	v_lshlrev_b32_e32 v38, 1, v6
	s_mov_b32 s4, s94

;     __device__ __forceinline__ float* ctl() const { return (float*)(ws + WS_CTL); }
;     __device__ __forceinline__ bf16_t* Win_t() const { return (bf16_t*)(ws + WS_WIN); }
;     __device__ __forceinline__ bf16_t* Wkv_t() const { return (bf16_t*)(ws + WS_WKV); }
;     __device__ __forceinline__ bf16_t* Wout_t() const { return (bf16_t*)(ws + WS_WOUT); }
;     __device__ __forceinline__ bf16_t* Wq_t() const { return (bf16_t*)(ws + WS_WQ); }
;     __device__ __forceinline__ bf16_t* Wo_t() const { return (bf16_t*)(ws + WS_WO); }
;     __device__ __forceinline__ bf16_t* W1_t() const { return (bf16_t*)(ws + WS_W1); }
;     __device__ __forceinline__ bf16_t* W2_t() const { return (bf16_t*)(ws + WS_W2); }
; __device__ __forceinline__ void p0_prologue(const Args& p, LAS unsigned char* lds, int G, int bid, int tid) {
;     ...
;     for (int it = gw; it < NITEMS; it += NGW) {
;         int r = it;
;         if (r < I_IN) { tr_item<1>(p.w_in(), DIN, p.Win_t(), DM, 0, scr, r / 48, r % 48, lane, nullptr, nullptr, nullptr, nullptr); continue; } r -= I_IN;
;         if (r < I_K) { tr_item<0>(p.xk_w(), DM, p.Wkv_t(), DM, 0, scr, r / 32, r % 32, lane, nullptr, nullptr, nullptr, nullptr); continue; } r -= I_K;
;         if (r < I_V) { tr_item<0>(p.xv_w(), DM, p.Wkv_t(), DM, DM, scr, r / 32, r % 32, lane, nullptr, nullptr, nullptr, nullptr); continue; } r -= I_V;
;         if (r < I_OUT) { tr_item<0>(p.w_out(), DM, p.Wout_t(), DM, 0, scr, r / 32, r % 32, lane, nullptr, nullptr, nullptr, nullptr); continue; } r -= I_OUT;
;         if (r < I_Q) { tr_item<2>(p.xq_w(), DM, p.Wq_t(), DM, 0, scr, r / 32, r % 32, lane, p.ln1_g(), p.ln1_b(), p.ctl() + CF_C1Q, p.ctl() + CF_C2Q); continue; } r -= I_Q;
;         if (r < I_O) { tr_item<0>(p.xo_w(), DM, p.Wo_t(), DM, 0, scr, r / 32, r % 32, lane, nullptr, nullptr, nullptr, nullptr); continue; } r -= I_O;
;         if (r < I_1) { tr_item<2>(p.w1(), DFF, p.W1_t(), DM, 0, scr, r / 128, r % 128, lane, p.ln2_g(), p.ln2_b(), p.ctl() + CF_C1H, p.ctl() + CF_C2H); continue; } r -= I_1;
;         tr_item<0>(p.w2(), DM, p.W2_t(), DFF, 0, scr, r / 32, r % 32, lane, nullptr, nullptr, nullptr, nullptr);
;     }
.LBB0_23:
	s_cmp_eq_u32 s98, 1
	s_cbranch_scc1 .Lpf_return
	v_lshrrev_b32_e32 v42, 6, v192
	v_lshl_add_u32 v41, s94, 3, v42
	s_movk_i32 s0, 0x1400
	v_cmp_gt_i32_e32 vcc, s0, v41
	s_and_saveexec_b64 s[0:1], vcc
	s_cbranch_execz .LBB0_74
	v_and_b32_e32 v2, 31, v192
	v_lshlrev_b32_e32 v30, 2, v2
	v_lshlrev_b32_e32 v2, 3, v192
	v_bfe_u32 v59, v192, 3, 3
	v_and_b32_e32 v18, 56, v2
	v_and_b32_e32 v0, 63, v192
	v_lshl_add_u32 v1, v42, 14, 0
	v_mul_u32_u24_e32 v2, 0x84, v18
	v_lshlrev_b32_e32 v3, 2, v59
	v_add_u32_e32 v57, v1, v30
	v_add3_u32 v60, v1, v2, v3
	v_mov_b32_e32 v1, 0x4a000
	v_mov_b32_e32 v2, 0x46000
	v_cmp_gt_u32_e32 vcc, 32, v0
	v_readlane_b32 s4, v242, 3
	v_bfe_u32 v56, v192, 5, 1
	v_cndmask_b32_e32 v0, v1, v2, vcc
	v_mov_b32_e32 v1, 0
	s_movk_i32 s2, 0x84
	v_mov_b32_e32 v31, v1
	v_readlane_b32 s17, v242, 16
	v_readlane_b32 s19, v242, 18
	v_mad_u32_u24 v58, v56, s2, v57
	v_readlane_b32 s16, v242, 15
	v_readlane_b32 s18, v242, 17
	s_waitcnt lgkmcnt(0)
	v_lshl_add_u64 v[10:11], s[74:75], 0, v[30:31]
	s_mov_b32 s2, s84
	v_readlane_b32 s72, v242, 19
	v_mov_b32_e32 v20, s19
	v_mov_b32_e32 v21, s17
	v_and_b32_e32 v24, 7, v192
	v_readlane_b32 s84, v242, 31
	v_lshlrev_b32_e32 v18, 1, v18
	v_mov_b32_e32 v19, v1
	v_cndmask_b32_e32 v21, v20, v21, vcc
	v_mov_b32_e32 v20, s18
	v_mov_b32_e32 v22, s16
	s_mov_b32 s84, s2
	v_lshl_add_u64 v[38:39], s[58:59], 0, v[18:19]
	s_mov_b64 s[2:3], 0x1700000
	v_cndmask_b32_e32 v20, v20, v22, vcc
	v_lshl_add_u64 v[22:23], s[58:59], 0, v[0:1]
	v_lshlrev_b32_e32 v0, 4, v24
	v_mov_b32_e32 v2, 0x45000
	v_mov_b32_e32 v3, 0x44000
	v_lshl_add_u64 v[18:19], v[38:39], 0, s[2:3]
	v_lshl_add_u64 v[34:35], s[58:59], 0, v[0:1]
	s_mov_b64 s[2:3], 0xf00000
	v_lshlrev_b32_e32 v64, 3, v24
	v_cndmask_b32_e32 v32, v2, v3, vcc
	v_mov_b32_e32 v33, v1
	v_lshl_add_u64 v[24:25], v[34:35], 0, s[2:3]
	s_mov_b64 s[2:3], 0xd00000
	v_readlane_b32 s5, v242, 4
	v_readlane_b32 s7, v242, 6
	v_readlane_b32 s8, v242, 7
	v_readlane_b32 s9, v242, 8
	v_readlane_b32 s10, v242, 9
	v_readlane_b32 s11, v242, 10
	v_readlane_b32 s12, v242, 11
	v_readlane_b32 s13, v242, 12
	v_readlane_b32 s14, v242, 13
	v_readlane_b32 s15, v242, 14
	v_readlane_b32 s86, v242, 33
	v_readlane_b32 s87, v242, 34
	v_lshl_add_u64 v[26:27], v[38:39], 0, s[2:3]
	v_lshl_add_u64 v[32:33], s[58:59], 0, v[32:33]
	s_mov_b64 s[2:3], 0xb00000
	v_lshl_add_u64 v[2:3], s[48:49], 0, v[30:31]
	v_lshl_add_u64 v[4:5], s[44:45], 0, v[30:31]
	v_readlane_b32 s6, v242, 5
	v_lshl_add_u64 v[6:7], s[14:15], 0, v[30:31]
	v_lshl_add_u64 v[8:9], s[8:9], 0, v[30:31]
	v_lshl_add_u64 v[12:13], s[12:13], 0, v[30:31]
	v_lshl_add_u64 v[14:15], s[10:11], 0, v[30:31]
	v_lshl_add_u64 v[16:17], s[86:87], 0, v[30:31]
	v_lshl_add_u64 v[22:23], v[22:23], 0, v[30:31]
	v_mov_b32_e32 v0, s7
	v_mov_b32_e32 v28, s5
	v_lshl_add_u64 v[30:31], v[32:33], 0, v[30:31]
	v_lshl_add_u64 v[32:33], v[34:35], 0, s[2:3]
	s_mov_b64 s[2:3], 0x900000
	v_cndmask_b32_e32 v29, v0, v28, vcc
	v_mov_b32_e32 v0, s6
	v_mov_b32_e32 v28, s4
	v_lshl_add_u64 v[34:35], v[38:39], 0, s[2:3]
	s_mov_b64 s[2:3], 0x500000
	v_cndmask_b32_e32 v28, v0, v28, vcc
	v_lshl_add_u64 v[36:37], v[38:39], 0, s[2:3]
	s_mov_b64 s[2:3], 0x200000
	v_lshlrev_b32_e32 v0, 1, v42
	s_lshl_b32 s20, s96, 3
	v_or_b32_e32 v61, 8, v59
	v_or_b32_e32 v62, 16, v59
	v_or_b32_e32 v63, 24, v59
	v_bitop3_b32 v65, v59, 15, 24 bitop3:0xc8
	v_lshl_add_u64 v[38:39], v[38:39], 0, s[2:3]
	v_add_u32_e32 v40, 0xfffff400, v41
	v_lshl_add_u32 v66, s94, 4, v0
	s_lshl_b32 s21, s96, 4
	v_mov_b32_e32 v67, 0x7ffffc00
	s_mov_b32 s22, 0x7fffffc0
	s_mov_b32 s23, 0x8000
	s_mov_b32 s24, 0x10000
	s_mov_b32 s25, 0x18000
	s_mov_b32 s26, 0x20000
	s_mov_b32 s27, 0x28000
	s_mov_b32 s28, 0x30000
	s_mov_b32 s29, 0x38000
	s_mov_b32 s30, 0xc8000
	s_mov_b32 s31, 0xd0000
	s_mov_b32 s33, 0xd8000
	s_mov_b32 s34, 0xe0000
	s_mov_b32 s35, 0xe8000
	s_mov_b32 s36, 0xf0000
	s_mov_b32 s37, 0xf8000
	s_movk_i32 s38, 0x400
	s_mov_b32 s39, 0x2aaaaaab
	s_movk_i32 s40, 0x1800
	s_movk_i32 s41, 0x1ff
	s_mov_b32 s42, 0x7fffffe0
	s_movk_i32 s43, 0xffe0
	s_movk_i32 s44, 0x13ff
	s_mov_b64 s[2:3], 0
	v_readlane_b32 s73, v242, 20
	v_readlane_b32 s74, v242, 21
	v_readlane_b32 s75, v242, 22
	v_readlane_b32 s76, v242, 23
	v_readlane_b32 s77, v242, 24
	v_readlane_b32 s78, v242, 25
	v_readlane_b32 s79, v242, 26
	v_readlane_b32 s80, v242, 27
	v_readlane_b32 s81, v242, 28
	v_readlane_b32 s82, v242, 29
	v_readlane_b32 s83, v242, 30
	v_readlane_b32 s85, v242, 32
	s_branch .LBB0_27

; __device__ __forceinline__ void xcd_barrier(const XcdBarrier& b) {
; __device__ __forceinline__ void p0_prologue(const Args& p, LAS unsigned char* lds, int G, int bid, int tid) {
;     ...
;     for (int it = bid; it < 256; it += G) poolfold_block(p, lds, it, tid);
;     for (int it = gw; it < NITEMS; it += NGW) {
;         int r = it;
;         if (r < I_IN) { tr_item<1>(p.w_in(), DIN, p.Win_t(), DM, 0, scr, r / 48, r % 48, lane, nullptr, nullptr, nullptr, nullptr); continue; } r -= I_IN;
;         if (r < I_K) { tr_item<0>(p.xk_w(), DM, p.Wkv_t(), DM, 0, scr, r / 32, r % 32, lane, nullptr, nullptr, nullptr, nullptr); continue; } r -= I_K;
;         if (r < I_V) { tr_item<0>(p.xv_w(), DM, p.Wkv_t(), DM, DM, scr, r / 32, r % 32, lane, nullptr, nullptr, nullptr, nullptr); continue; } r -= I_V;
;         if (r < I_OUT) { tr_item<0>(p.w_out(), DM, p.Wout_t(), DM, 0, scr, r / 32, r % 32, lane, nullptr, nullptr, nullptr, nullptr); continue; } r -= I_OUT;
;         if (r < I_Q) { tr_item<2>(p.xq_w(), DM, p.Wq_t(), DM, 0, scr, r / 32, r % 32, lane, p.ln1_g(), p.ln1_b(), p.ctl() + CF_C1Q, p.ctl() + CF_C2Q); continue; } r -= I_Q;
;         if (r < I_O) { tr_item<0>(p.xo_w(), DM, p.Wo_t(), DM, 0, scr, r / 32, r % 32, lane, nullptr, nullptr, nullptr, nullptr); continue; } r -= I_O;
;         if (r < I_1) { tr_item<2>(p.w1(), DFF, p.W1_t(), DM, 0, scr, r / 128, r % 128, lane, p.ln2_g(), p.ln2_b(), p.ctl() + CF_C1H, p.ctl() + CF_C2H); continue; } r -= I_1;
;         tr_item<0>(p.w2(), DM, p.W2_t(), DFF, 0, scr, r / 32, r % 32, lane, nullptr, nullptr, nullptr, nullptr);
;     }
;     const int gt = bid * 512 + tid, NT = G * 512;
;     ...
;     CVT_REGION(p.x_prompt(), p.XB(), NPT * (DM / 4));
;     CVT_REGION(p.x_sample(), p.XB() + (size_t)NPT * DM, NST * (DM / 4));
;     CVT_REGION(p.mem_prompt(), p.MB(), MEMROWS * (DM / 4));
;     ...
;     for (int i = gt; i < DECB * 3328; i += NT) { const int sb = i / 3328, o = i % 3328; __builtin_nontemporal_store(__builtin_nontemporal_load((const f32x4*)(p.state_conv() + (size_t)sb * 15360 + 2048) + o), (f32x4*)(p.out() + OCS + (size_t)sb * 15360) + o); }
;     for (int i = gt; i < DECB * 1408; i += NT) { const int sb = i / 1408, o = i % 1408; __builtin_nontemporal_store(__builtin_nontemporal_load((const f32x4*)(p.state_pool() + (size_t)sb * 7680 + 2048) + o), (f32x4*)(p.out() + OPS + (size_t)sb * 7680) + o); }
.LBB0_98:
	s_or_b64 exec, exec, s[4:5]
	s_bitcmp1_b32 s94, 0
	s_cbranch_scc0 .Lpf_return
	s_cmpk_gt_i32 s94, 0xff
	s_cbranch_scc1 .Lpf_return
	s_mov_b32 s98, 1
	s_load_dwordx2 s[70:71], s[100:101], 0x68
	s_load_dwordx2 s[72:73], s[100:101], 0x70
	s_load_dwordx2 s[74:75], s[100:101], 0x78
	s_waitcnt lgkmcnt(0)
	s_barrier
	s_branch .Lpf_entry
.Lpf_return:
	s_mov_b32 s98, 0
	s_cmp_lt_i32 s89, 2
	s_cbranch_scc1 .LBB0_158
	s_waitcnt vmcnt(0)
	s_waitcnt lgkmcnt(0)
	s_barrier
	s_mov_b64 s[0:1], exec
	v_readlane_b32 s2, v242, 1
	v_readlane_b32 s3, v242, 2
	s_and_b64 s[2:3], s[0:1], s[2:3]
	s_mov_b64 exec, s[2:3]
	s_cbranch_execz .LBB0_157
	s_add_i32 s2, 0, 0x21fc0
	v_mov_b32_e32 v0, s2
	s_waitcnt vmcnt(0) expcnt(0) lgkmcnt(0)
	ds_read_b32 v2, v0
	s_add_i32 s2, 0, 0x21fc4
	v_mov_b32_e32 v0, s2
	ds_read_b32 v0, v0
	s_waitcnt lgkmcnt(1)
	v_cmp_ne_u32_e32 vcc, 0, v2
	s_cbranch_vccnz .LBB0_121
	v_readlane_b32 s2, v242, 0
	s_mul_i32 s33, s97, s2
	s_add_u32 s2, s58, 0x50200
	s_addc_u32 s3, s59, 0
	s_add_u32 s4, s58, 0x50400
	s_addc_u32 s5, s59, 0
	s_add_u32 s6, s58, 0x50500
	s_addc_u32 s7, s59, 0
	s_add_u32 s8, s58, 0x50600
	s_addc_u32 s9, s59, 0
	s_add_u32 s10, s58, 0x50700
	s_addc_u32 s11, s59, 0
	s_add_u32 s12, s58, 0x50800
	s_addc_u32 s13, s59, 0
	s_add_u32 s14, s58, 0x50900
	s_addc_u32 s15, s59, 0
	s_add_u32 s16, s58, 0x50a00
	s_addc_u32 s17, s59, 0
	s_add_u32 s18, s58, 0x50b00
	s_addc_u32 s19, s59, 0
	s_add_u32 s20, s58, 0x50c00
	s_addc_u32 s21, s59, 0
	s_add_u32 s22, s58, 0x50d00
	s_addc_u32 s23, s59, 0
	s_add_u32 s24, s58, 0x50e00
	s_addc_u32 s25, s59, 0
	s_add_u32 s26, s58, 0x50f00
	s_addc_u32 s27, s59, 0
	s_add_u32 s28, s58, 0x51000
	s_addc_u32 s29, s59, 0
	s_add_u32 s30, s58, 0x51100
	s_addc_u32 s31, s59, 0
	s_add_u32 s34, s58, 0x51200
	s_addc_u32 s35, s59, 0
	s_add_u32 s36, s58, 0x51300
	s_mul_i32 s33, s33, s96
	s_addc_u32 s37, s59, 0
	s_mov_b32 s40, 1
	v_mov_b32_e32 v16, 0
	s_branch .LBB0_109
